# v086 with the next tile's K fragment reads moved directly behind the last P·V MFMA gap (ahead of the last adds and conversions)
# speedup vs baseline: 1.0026x; 1.0004x over previous
; #define ALAS __attribute__((address_space(3)))
; template <bool WIN> ...
;     ...
;                 for (int ds = 0; ds < 4; ++ds) { ka[2 * ds] = *(const ALAS bf16x8*)(sb + kx[ds]); ka[2 * ds + 1] = *(const ALAS bf16x8*)(sb + kx[ds] + 4096); }
;     ...
;             float ls0 = 0.f, ls1 = 0.f;
;     ...
;             union PFU { u32x4 u; bf16x8 b; };
;             PFU p0, p1, p2, p3;
;             AT_EXP(s0, 0, p0);
; #pragma unroll
;             for (int kk = 0; kk < 2; ++kk)
; #pragma unroll
;                 for (int db = 0; db < NDB; ++db) vc[kk * NDB + db] = *(const ALAS bf16x8*)(sb + vx[kk + 2] + db * 4096);
;             __builtin_amdgcn_sched_barrier(0);
; #pragma unroll
;             for (int db = 0; db < NDB; ++db) o[db] = __builtin_amdgcn_mfma_f32_32x32x16_bf16(va[db], p0.b, o[db], 0, 0, 0);
;             AT_EXP(s0, 8, p1);
;             __builtin_amdgcn_sched_barrier(0);
; #pragma unroll
;             for (int db = 0; db < NDB; ++db) o[db] = __builtin_amdgcn_mfma_f32_32x32x16_bf16(va[NDB + db], p1.b, o[db], 0, 0, 0);
;             AT_EXP(s1, 0, p2);
;             __builtin_amdgcn_sched_barrier(0);
; #pragma unroll
;             for (int db = 0; db < NDB; ++db) o[db] = __builtin_amdgcn_mfma_f32_32x32x16_bf16(vc[db], p2.b, o[db], 0, 0, 0);
;             AT_EXP(s1, 8, p3);
;             __builtin_amdgcn_sched_barrier(0);
; #pragma unroll
;             for (int db = 0; db < NDB; ++db) o[db] = __builtin_amdgcn_mfma_f32_32x32x16_bf16(vc[NDB + db], p3.b, o[db], 0, 0, 0);
;             __builtin_amdgcn_sched_barrier(0);
;     ...
;             l_run += ls0 + ls1;
.LSPp_pv:
	s_cmp_eq_u32 s86, 0
	s_cbranch_scc1 .LSPp_pure
	s_waitcnt lgkmcnt(4)
	v_mfma_f32_32x32x16_bf16 v[50:65], v[130:133], v[238:241], v[50:65]
	v_exp_f32_e32 v98, v98
	v_exp_f32_e32 v99, v99
	v_mfma_f32_32x32x16_bf16 v[34:49], v[134:137], v[238:241], v[34:49]
	v_exp_f32_e32 v100, v100
	v_exp_f32_e32 v101, v101
	v_mfma_f32_32x32x16_bf16 v[18:33], v[138:141], v[238:241], v[18:33]
	v_exp_f32_e32 v102, v102
	v_exp_f32_e32 v103, v103
	v_add_f32_e32 v228, v98, v100
	v_add_f32_e32 v229, v99, v101
	v_mfma_f32_32x32x16_bf16 v[2:17], v[142:145], v[238:241], v[2:17]
	v_exp_f32_e32 v104, v104
	v_exp_f32_e32 v105, v105
	v_add_f32_e32 v228, v228, v102
	v_add_f32_e32 v229, v229, v103
	v_add3_u32 v236, s99, v183, v187
	ds_read_b128 v[130:133], v236 offset:16384
	ds_read_b128 v[134:137], v236 offset:20480
	ds_read_b128 v[138:141], v236 offset:24576
	ds_read_b128 v[142:145], v236 offset:28672
	s_waitcnt lgkmcnt(4)
	v_mfma_f32_32x32x16_bf16 v[50:65], v[146:149], v[242:245], v[50:65]
	v_exp_f32_e32 v106, v106
	v_exp_f32_e32 v107, v107
	v_add_f32_e32 v228, v228, v104
	v_add_f32_e32 v229, v229, v105
	v_cvt_pk_bf16_f32 v238, v98, v99
	v_lshl_add_u64 v[174:175], v[174:175], 0, s[60:61]
	s_add_i32 s87, s85, 0xffff8000
	s_and_b32 s87, s87, 0x18000
	v_mfma_f32_32x32x16_bf16 v[34:49], v[150:153], v[242:245], v[34:49]
	v_exp_f32_e32 v108, v108
	v_exp_f32_e32 v109, v109
	v_add_f32_e32 v228, v228, v106
	v_add_f32_e32 v229, v229, v107
	v_cvt_pk_bf16_f32 v239, v100, v101
	v_lshl_add_u64 v[172:173], v[172:173], 0, s[48:49]
	s_add_i32 s98, s85, 0x10000
	s_and_b32 s98, s98, 0x18000
	v_mfma_f32_32x32x16_bf16 v[18:33], v[154:157], v[242:245], v[18:33]
	v_exp_f32_e32 v110, v110
	v_exp_f32_e32 v111, v111
	v_add_f32_e32 v228, v228, v108
	v_add_f32_e32 v229, v229, v109
	v_cvt_pk_bf16_f32 v240, v102, v103
	v_lshl_add_u64 v[208:209], v[174:175], 0, s[40:41]
	s_add_i32 s98, s98, s20
	s_add_i32 s101, s85, 0x8000
	v_mfma_f32_32x32x16_bf16 v[2:17], v[158:161], v[242:245], v[2:17]
	v_exp_f32_e32 v112, v112
	v_exp_f32_e32 v113, v113
	v_add_f32_e32 v228, v228, v110
	v_add_f32_e32 v229, v229, v111
	v_cvt_pk_bf16_f32 v241, v104, v105
	v_lshl_add_u64 v[210:211], v[172:173], 0, s[40:41]
	s_and_b32 s101, s101, 0x18000
	s_add_i32 s101, s101, s20
	v_add3_u32 v237, s99, v190, v187
	ds_read_b128 v[146:149], v237 offset:16384
	ds_read_b128 v[150:153], v237 offset:20480
	ds_read_b128 v[154:157], v237 offset:24576
	ds_read_b128 v[158:161], v237 offset:28672
	s_waitcnt lgkmcnt(4)
	v_mfma_f32_32x32x16_bf16 v[50:65], v[130:133], v[246:249], v[50:65]
	v_exp_f32_e32 v82, v82
	v_exp_f32_e32 v83, v83
	v_add_f32_e32 v228, v228, v112
	v_add_f32_e32 v229, v229, v113
	v_cvt_pk_bf16_f32 v242, v106, v107
	v_add3_u32 v212, s87, v178, v162
	s_add_i32 s99, s81, s83
	s_add_i32 s99, s99, 64
	v_mfma_f32_32x32x16_bf16 v[34:49], v[134:137], v[246:249], v[34:49]
	v_exp_f32_e32 v84, v84
	v_exp_f32_e32 v85, v85
	v_add_f32_e32 v228, v228, v82
	v_add_f32_e32 v229, v229, v83
	v_cvt_pk_bf16_f32 v243, v108, v109
	v_add3_u32 v213, s87, v180, v162
	s_sub_i32 m0, s82, 64
	s_max_i32 s99, s99, m0
	v_mfma_f32_32x32x16_bf16 v[18:33], v[138:141], v[246:249], v[18:33]
	v_exp_f32_e32 v86, v86
	v_exp_f32_e32 v87, v87
	v_add_f32_e32 v228, v228, v84
	v_add_f32_e32 v229, v229, v85
	v_cvt_pk_bf16_f32 v244, v110, v111
	v_add3_u32 v214, s87, v182, v162
	s_add_i32 m0, s83, 64
	s_cmp_gt_i32 m0, s78
	v_mfma_f32_32x32x16_bf16 v[2:17], v[142:145], v[246:249], v[2:17]
	v_exp_f32_e32 v88, v88
	v_exp_f32_e32 v89, v89
	v_add_f32_e32 v228, v228, v86
	v_add_f32_e32 v229, v229, v87
	v_cvt_pk_bf16_f32 v245, v112, v113
	v_add3_u32 v215, s87, v184, v162
	s_cselect_b32 m0, s80, s79
	s_cmpk_lt_i32 s99, 0x80
	s_waitcnt lgkmcnt(0)
	v_mfma_f32_32x32x16_bf16 v[50:65], v[146:149], v[250:253], v[50:65]
	v_exp_f32_e32 v90, v90
	v_exp_f32_e32 v91, v91
	v_add_f32_e32 v228, v228, v88
	v_add_f32_e32 v229, v229, v89
	v_cvt_pk_bf16_f32 v246, v82, v83
	s_cselect_b32 s65, 1, 0
	s_cselect_b32 m0, 0, m0
	v_mfma_f32_32x32x16_bf16 v[34:49], v[150:153], v[250:253], v[34:49]
	v_exp_f32_e32 v92, v92
	v_exp_f32_e32 v93, v93
	v_add_f32_e32 v228, v228, v90
	v_add_f32_e32 v229, v229, v91
	v_cvt_pk_bf16_f32 v247, v84, v85
	s_add_i32 s99, s85, 0xffff0000
	s_and_b32 s99, s99, 0x18000
	v_mfma_f32_32x32x16_bf16 v[18:33], v[154:157], v[250:253], v[18:33]
	v_exp_f32_e32 v94, v94
	v_exp_f32_e32 v95, v95
	v_add_f32_e32 v228, v228, v92
	v_add_f32_e32 v229, v229, v93
	v_cvt_pk_bf16_f32 v248, v86, v87
	v_mfma_f32_32x32x16_bf16 v[2:17], v[158:161], v[250:253], v[2:17]
	v_exp_f32_e32 v96, v96
	v_exp_f32_e32 v97, v97
	v_add_f32_e32 v228, v228, v94
	v_add_f32_e32 v229, v229, v95
	v_cvt_pk_bf16_f32 v249, v88, v89
	ds_read_b128 v[130:133], v212
	ds_read_b128 v[134:137], v212 offset:4096
	ds_read_b128 v[138:141], v213
	ds_read_b128 v[142:145], v213 offset:4096
	ds_read_b128 v[146:149], v214
	ds_read_b128 v[150:153], v214 offset:4096
	ds_read_b128 v[158:161], v215
	ds_read_b128 v[204:207], v215 offset:4096
	v_add_f32_e32 v228, v228, v96
	v_add_f32_e32 v229, v229, v97
	v_cvt_pk_bf16_f32 v250, v90, v91
	v_cvt_pk_bf16_f32 v251, v92, v93
	v_cvt_pk_bf16_f32 v252, v94, v95
	v_cvt_pk_bf16_f32 v253, v96, v97
	v_add_f32_e32 v228, v228, v229
	v_cmp_nge_f32_e32 vcc, 0x53800000, v228
	s_cbranch_vccnz .LSPp_redo
	s_add_i32 s86, s86, 1
	s_add_i32 s85, s85, 0x8000
	s_addk_i32 s84, 0x100
	s_add_i32 s83, s83, 64
	s_sub_i32 s82, s82, 64
	v_add_f32_e32 v0, v0, v228
	s_cmpk_eq_u32 s84, 0x8000
	s_cbranch_scc0 .LSPp_top
	s_branch .LSPp_exit

; #define ALAS __attribute__((address_space(3)))
; template <bool WIN> ...
;     ...
;                 for (int ds = 0; ds < 4; ++ds) { ka[2 * ds] = *(const ALAS bf16x8*)(sb + kx[ds]); ka[2 * ds + 1] = *(const ALAS bf16x8*)(sb + kx[ds] + 4096); }
;     ...
;             float ls0 = 0.f, ls1 = 0.f;
;     ...
;             union PFU { u32x4 u; bf16x8 b; };
;             PFU p0, p1, p2, p3;
;             AT_EXP(s0, 0, p0);
; #pragma unroll
;             for (int kk = 0; kk < 2; ++kk)
; #pragma unroll
;                 for (int db = 0; db < NDB; ++db) vc[kk * NDB + db] = *(const ALAS bf16x8*)(sb + vx[kk + 2] + db * 4096);
;             __builtin_amdgcn_sched_barrier(0);
; #pragma unroll
;             for (int db = 0; db < NDB; ++db) o[db] = __builtin_amdgcn_mfma_f32_32x32x16_bf16(va[db], p0.b, o[db], 0, 0, 0);
;             AT_EXP(s0, 8, p1);
;             __builtin_amdgcn_sched_barrier(0);
; #pragma unroll
;             for (int db = 0; db < NDB; ++db) o[db] = __builtin_amdgcn_mfma_f32_32x32x16_bf16(va[NDB + db], p1.b, o[db], 0, 0, 0);
;             AT_EXP(s1, 0, p2);
;             __builtin_amdgcn_sched_barrier(0);
; #pragma unroll
;             for (int db = 0; db < NDB; ++db) o[db] = __builtin_amdgcn_mfma_f32_32x32x16_bf16(vc[db], p2.b, o[db], 0, 0, 0);
;             AT_EXP(s1, 8, p3);
;             __builtin_amdgcn_sched_barrier(0);
; #pragma unroll
;             for (int db = 0; db < NDB; ++db) o[db] = __builtin_amdgcn_mfma_f32_32x32x16_bf16(vc[NDB + db], p3.b, o[db], 0, 0, 0);
;             __builtin_amdgcn_sched_barrier(0);
;     ...
;             l_run += ls0 + ls1;
.LSPs_pv:
	s_cmp_eq_u32 s79, 0
	s_cbranch_scc1 .LSPs_pure
	s_waitcnt lgkmcnt(4)
	v_mfma_f32_32x32x16_bf16 v[50:65], v[130:133], v[238:241], v[50:65]
	v_exp_f32_e32 v98, v98
	v_exp_f32_e32 v99, v99
	v_mfma_f32_32x32x16_bf16 v[34:49], v[134:137], v[238:241], v[34:49]
	v_exp_f32_e32 v100, v100
	v_exp_f32_e32 v101, v101
	v_mfma_f32_32x32x16_bf16 v[18:33], v[138:141], v[238:241], v[18:33]
	v_exp_f32_e32 v102, v102
	v_exp_f32_e32 v103, v103
	v_add_f32_e32 v228, v98, v100
	v_add_f32_e32 v229, v99, v101
	v_mfma_f32_32x32x16_bf16 v[2:17], v[142:145], v[238:241], v[2:17]
	v_exp_f32_e32 v104, v104
	v_exp_f32_e32 v105, v105
	v_add_f32_e32 v228, v228, v102
	v_add_f32_e32 v229, v229, v103
	v_add3_u32 v236, s99, v183, v187
	ds_read_b128 v[130:133], v236 offset:16384
	ds_read_b128 v[134:137], v236 offset:20480
	ds_read_b128 v[138:141], v236 offset:24576
	ds_read_b128 v[142:145], v236 offset:28672
	s_waitcnt lgkmcnt(4)
	v_mfma_f32_32x32x16_bf16 v[50:65], v[146:149], v[242:245], v[50:65]
	v_exp_f32_e32 v106, v106
	v_exp_f32_e32 v107, v107
	v_add_f32_e32 v228, v228, v104
	v_add_f32_e32 v229, v229, v105
	v_cvt_pk_bf16_f32 v238, v98, v99
	v_lshl_add_u64 v[174:175], v[174:175], 0, s[60:61]
	s_add_i32 s80, s78, 0xffff8000
	s_and_b32 s80, s80, 0x18000
	v_mfma_f32_32x32x16_bf16 v[34:49], v[150:153], v[242:245], v[34:49]
	v_exp_f32_e32 v108, v108
	v_exp_f32_e32 v109, v109
	v_add_f32_e32 v228, v228, v106
	v_add_f32_e32 v229, v229, v107
	v_cvt_pk_bf16_f32 v239, v100, v101
	v_lshl_add_u64 v[172:173], v[172:173], 0, s[48:49]
	s_add_i32 s98, s78, 0x10000
	s_and_b32 s98, s98, 0x18000
	v_mfma_f32_32x32x16_bf16 v[18:33], v[154:157], v[242:245], v[18:33]
	v_exp_f32_e32 v110, v110
	v_exp_f32_e32 v111, v111
	v_add_f32_e32 v228, v228, v108
	v_add_f32_e32 v229, v229, v109
	v_cvt_pk_bf16_f32 v240, v102, v103
	v_lshl_add_u64 v[208:209], v[174:175], 0, s[40:41]
	s_add_i32 s98, s98, s29
	s_add_i32 s101, s78, 0x8000
	v_mfma_f32_32x32x16_bf16 v[2:17], v[158:161], v[242:245], v[2:17]
	v_exp_f32_e32 v112, v112
	v_exp_f32_e32 v113, v113
	v_add_f32_e32 v228, v228, v110
	v_add_f32_e32 v229, v229, v111
	v_cvt_pk_bf16_f32 v241, v104, v105
	v_lshl_add_u64 v[210:211], v[172:173], 0, s[40:41]
	s_and_b32 s101, s101, 0x18000
	s_add_i32 s101, s101, s29
	v_add3_u32 v237, s99, v190, v187
	ds_read_b128 v[146:149], v237 offset:16384
	ds_read_b128 v[150:153], v237 offset:20480
	ds_read_b128 v[154:157], v237 offset:24576
	ds_read_b128 v[158:161], v237 offset:28672
	s_waitcnt lgkmcnt(4)
	v_mfma_f32_32x32x16_bf16 v[50:65], v[130:133], v[246:249], v[50:65]
	v_exp_f32_e32 v82, v82
	v_exp_f32_e32 v83, v83
	v_add_f32_e32 v228, v228, v112
	v_add_f32_e32 v229, v229, v113
	v_cvt_pk_bf16_f32 v242, v106, v107
	v_add3_u32 v212, s80, v178, v162
	s_add_i32 s99, s76, 64
	s_cmp_gt_u32 s99, s28
	v_mfma_f32_32x32x16_bf16 v[34:49], v[134:137], v[246:249], v[34:49]
	v_exp_f32_e32 v84, v84
	v_exp_f32_e32 v85, v85
	v_add_f32_e32 v228, v228, v82
	v_add_f32_e32 v229, v229, v83
	v_cvt_pk_bf16_f32 v243, v108, v109
	v_add3_u32 v213, s80, v180, v162
	s_cselect_b32 m0, s31, s30
	s_cmp_lt_u32 s99, s33
	v_mfma_f32_32x32x16_bf16 v[18:33], v[138:141], v[246:249], v[18:33]
	v_exp_f32_e32 v86, v86
	v_exp_f32_e32 v87, v87
	v_add_f32_e32 v228, v228, v84
	v_add_f32_e32 v229, v229, v85
	v_cvt_pk_bf16_f32 v244, v110, v111
	v_add3_u32 v214, s80, v182, v162
	s_cselect_b32 s65, 1, 0
	s_cmp_gt_i32 s99, s67
	v_mfma_f32_32x32x16_bf16 v[2:17], v[142:145], v[246:249], v[2:17]
	v_exp_f32_e32 v88, v88
	v_exp_f32_e32 v89, v89
	v_add_f32_e32 v228, v228, v86
	v_add_f32_e32 v229, v229, v87
	v_cvt_pk_bf16_f32 v245, v112, v113
	v_add3_u32 v215, s80, v184, v162
	s_cselect_b32 s65, s65, 0
	s_cmp_lg_u32 s65, 0
	s_waitcnt lgkmcnt(0)
	v_mfma_f32_32x32x16_bf16 v[50:65], v[146:149], v[250:253], v[50:65]
	v_exp_f32_e32 v90, v90
	v_exp_f32_e32 v91, v91
	v_add_f32_e32 v228, v228, v88
	v_add_f32_e32 v229, v229, v89
	v_cvt_pk_bf16_f32 v246, v82, v83
	s_cselect_b32 m0, 0, m0
	s_add_i32 s99, s78, 0xffff0000
	v_mfma_f32_32x32x16_bf16 v[34:49], v[150:153], v[250:253], v[34:49]
	v_exp_f32_e32 v92, v92
	v_exp_f32_e32 v93, v93
	v_add_f32_e32 v228, v228, v90
	v_add_f32_e32 v229, v229, v91
	v_cvt_pk_bf16_f32 v247, v84, v85
	s_and_b32 s99, s99, 0x18000
	v_mfma_f32_32x32x16_bf16 v[18:33], v[154:157], v[250:253], v[18:33]
	v_exp_f32_e32 v94, v94
	v_exp_f32_e32 v95, v95
	v_add_f32_e32 v228, v228, v92
	v_add_f32_e32 v229, v229, v93
	v_cvt_pk_bf16_f32 v248, v86, v87
	v_mfma_f32_32x32x16_bf16 v[2:17], v[158:161], v[250:253], v[2:17]
	v_exp_f32_e32 v96, v96
	v_exp_f32_e32 v97, v97
	v_add_f32_e32 v228, v228, v94
	v_add_f32_e32 v229, v229, v95
	v_cvt_pk_bf16_f32 v249, v88, v89
	ds_read_b128 v[130:133], v212
	ds_read_b128 v[134:137], v212 offset:4096
	ds_read_b128 v[138:141], v213
	ds_read_b128 v[142:145], v213 offset:4096
	ds_read_b128 v[146:149], v214
	ds_read_b128 v[150:153], v214 offset:4096
	ds_read_b128 v[158:161], v215
	ds_read_b128 v[204:207], v215 offset:4096
	v_add_f32_e32 v228, v228, v96
	v_add_f32_e32 v229, v229, v97
	v_cvt_pk_bf16_f32 v250, v90, v91
	v_cvt_pk_bf16_f32 v251, v92, v93
	v_cvt_pk_bf16_f32 v252, v94, v95
	v_cvt_pk_bf16_f32 v253, v96, v97
	v_add_f32_e32 v228, v228, v229
	v_cmp_nge_f32_e32 vcc, 0x53800000, v228
	s_cbranch_vccnz .LSPs_redo
	s_add_i32 s79, s79, 1
	s_add_i32 s78, s78, 0x8000
	s_addk_i32 s77, 0x100
	s_add_i32 s76, s76, 64
	v_add_f32_e32 v0, v0, v228
	s_cmpk_eq_i32 s77, 0x2000
	s_cbranch_scc0 .LSPs_top
	s_branch .LSPs_exit
